# v100 + nt on P2's q loads and on the second-touch x loads of P6's epilogue
# speedup vs baseline: 1.0025x; 1.0025x over previous
; #define LAS __attribute__((address_space(3)))
; __device__ __forceinline__ void attn_phase(LAS unsigned char* lds, const u16* ZB, u16* OG, float* LSE, int bid, int G) {
;     const int tid = threadIdx.x, lane = tid & 63, w = __builtin_amdgcn_readfirstlane(tid >> 6), l15 = lane & 15, q4 = lane >> 4, sb = w >> 2, wq = w & 3;
;     constexpr int KP = 72;
;     LAS u16* KI = (LAS u16*)lds; LAS u16* VI = (LAS u16*)(lds + 384 * KP * 2);
;     u32x4 kr[6], vr[6]; bf16x8 qn[2][2];
;     ...
;     const bool xl = (G == 256); const int ustep = xl ? 32 : G, ubase = xl ? (bid & 7) * 192 : 0, ulim = xl ? ubase + 192 : 1536;
;     { const int u0 = ubase + (xl ? (bid >> 3) : bid); AT_LOAD((u0 < ulim ? u0 : ulim - 1)); }
.LBB0_207:
	s_cmp_ge_i32 s22, s58
	s_cbranch_scc1 .LBB0_263
	s_bfe_u32 s21, s19, 0x20006
	s_lshr_b32 s20, s19, 6
	s_lshl_b32 s59, s21, 5
	s_add_u32 s60, s78, 0x1b00000
	s_addc_u32 s61, s79, 0
	s_and_b64 s[0:1], s[10:11], exec
	s_cselect_b32 s62, 32, s80
	s_ashr_i32 s13, s12, 31
	s_lshl_b64 s[0:1], s[12:13], 21
	s_add_u32 s0, s6, s0
	s_addc_u32 s1, s7, s1
	v_and_b32_e32 v134, 48, v188
	v_mov_b32_e32 v135, 0
	s_lshr_b32 s63, s19, 8
	v_lshl_add_u64 v[48:49], s[0:1], 0, v[134:135]
	s_and_b64 s[0:1], s[4:5], exec
	s_cselect_b32 s0, s63, 0
	s_add_i32 s18, s18, s0
	s_add_u32 s0, s8, s18
	s_addc_u32 s1, s9, 0
	s_add_i32 s8, s63, s17
	s_lshl_b32 s8, s8, 7
	s_and_b64 s[4:5], s[4:5], exec
	v_and_b32_e32 v152, 15, v188
	s_cselect_b32 s4, 0, s8
	v_or_b32_e32 v50, s4, v152
	v_or_b32_e32 v50, s59, v50
	v_lshl_add_u64 v[136:137], s[6:7], 0, v[134:135]
	v_add_u32_e32 v138, 0, v134
	v_or_b32_e32 v134, 16, v50
	v_mov_b32_e32 v51, v135
	v_lshlrev_b64 v[54:55], s16, v[134:135]
	v_lshlrev_b64 v[50:51], s16, v[50:51]
	v_lshl_add_u64 v[54:55], s[0:1], 0, v[54:55]
	v_lshl_add_u64 v[50:51], s[0:1], 0, v[50:51]
	v_lshlrev_b64 v[54:55], 7, v[54:55]
	v_lshlrev_b64 v[50:51], 7, v[50:51]
	v_lshl_add_u64 v[54:55], v[48:49], 0, v[54:55]
	v_lshl_add_u64 v[48:49], v[48:49], 0, v[50:51]
	global_load_dwordx4 v[64:67], v[54:55], off offset:64 nt
	global_load_dwordx4 v[68:71], v[54:55], off nt
	global_load_dwordx4 v[72:75], v[48:49], off offset:64 nt
	global_load_dwordx4 v[76:79], v[48:49], off nt
	v_and_b32_e32 v52, 24, v52
	s_mulk_i32 s20, 0x1200
	v_lshl_add_u32 v50, v53, 1, 0
	v_add_u32_e32 v142, 0, v52
	v_mul_u32_u24_e32 v52, 0x48, v139
	s_lshl_b32 s69, s63, 7
	s_add_i32 s0, s20, 0
	v_lshl_add_u32 v155, v52, 1, v50
	v_mul_u32_u24_e32 v52, 0x48, v143
	s_add_i32 s70, s69, 0xffffff80
	s_add_i32 s0, s0, 0x1b000
	v_bfe_u32 v49, v188, 4, 2
	v_lshl_add_u32 v156, v52, 1, v50
	v_mul_u32_u24_e32 v52, 0x48, v147
	s_cmp_eq_u32 s21, 3
	v_lshlrev_b32_e32 v51, 2, v49
	v_lshl_add_u32 v158, v52, 1, v50
	v_mul_u32_u24_e32 v52, 0x48, v151
	s_cselect_b64 s[34:35], -1, 0
	s_add_i32 s71, s59, 32
	v_lshl_add_u32 v160, v52, 1, v50
	v_or_b32_e32 v50, 1, v51
	s_cmp_gt_u32 s21, 1
	v_and_b32_e32 v48, 63, v188
	v_mov_b32_e32 v133, v135
	v_bfe_u32 v53, v188, 2, 2
	v_bfe_u32 v154, v188, 3, 3
	v_cmp_lt_u32_e64 s[8:9], v50, v152
	v_or_b32_e32 v50, 2, v51
	v_or_b32_e32 v52, 3, v51
	s_cselect_b64 s[40:41], -1, 0
	s_add_i32 s72, s59, 64
	v_lshl_add_u64 v[140:141], s[6:7], 0, v[132:133]
	v_or_b32_e32 v153, v51, v53
	v_cmp_gt_u32_e64 s[4:5], 16, v48
	v_mul_u32_u24_e32 v48, 0x90, v154
	v_cmp_lt_u32_e64 s[6:7], v51, v152
	v_cmp_lt_u32_e64 s[10:11], v50, v152
	v_cmp_lt_u32_e64 s[12:13], v52, v152
	v_cmp_gt_u32_e64 s[14:15], v51, v152
	v_cmp_gt_u32_e64 s[16:17], v50, v152
	v_cmp_gt_u32_e64 s[18:19], v52, v152
	v_mul_u32_u24_e32 v50, 0x90, v152
	v_lshl_add_u32 v49, v49, 3, s0
	v_add_u32_e32 v51, s0, v132
	s_cmp_lg_u32 s21, 0
	v_mbcnt_lo_u32_b32 v52, -1, 0
	s_mov_b32 s37, 0
	s_movk_i32 s68, 0x90
	v_add_u32_e32 v157, 0x4800, v155
	v_add_u32_e32 v159, 0x9000, v155
	v_or_b32_e32 v161, 8, v154
	v_or_b32_e32 v162, 16, v154
	v_or_b32_e32 v163, 24, v154
	s_cselect_b64 s[42:43], -1, 0
	s_add_i32 s73, s59, 0x60
	s_or_b32 s86, s59, 0x80
	v_or_b32_e32 v164, s59, v152
	s_lshl_b32 s87, s22, 1
	s_lshl_b32 s88, s62, 1
	s_mov_b32 s89, 0xff800000
	v_mbcnt_hi_u32_b32 v165, -1, v52
	v_add_u32_e32 v166, v51, v48
	v_mov_b32_e32 v167, 0xff800000
	v_add_u32_e32 v168, v49, v50
	s_branch .LBB0_210

; #define LAS __attribute__((address_space(3)))
; __device__ __forceinline__ f32x4 mfma16(bf16x8 a, bf16x8 b, f32x4 c) { return __builtin_amdgcn_mfma_f32_16x16x32_bf16(a, b, c, 0, 0, 0); }
; __device__ __forceinline__ void attn_phase(LAS unsigned char* lds, const u16* ZB, u16* OG, float* LSE, int bid, int G) {
;     ...
;         for (int p = 0; p < 5; ++p) { const int a = wq + p; const bool on = prev_ok || a >= 4;
; #pragma unroll
;             for (int t = 0; t < 2; ++t) {
;                 if (on) { const int j0 = 32 * a + 16 * t, k = 2 * p + t; f32x4 s0 = (f32x4){0.f, 0.f, 0.f, 0.f}, s1 = (f32x4){0.f, 0.f, 0.f, 0.f};
; #pragma unroll
;                     for (int ds = 0; ds < 2; ++ds) { const bf16x8 kf = *(const LAS bf16x8*)(KI + (wbase + j0 + l15) * KP + 32 * ds + 8 * q4); if (k <= 8) s0 = mfma16(kf, qf[0][ds], s0); if (k >= 1) s1 = mfma16(kf, qf[1][ds], s1); }
; #pragma unroll
;                     for (int i = 0; i < 4; ++i) { const int kk = 4 * q4 + i;
;                         if (k == 0) s0[i] = (kk >= l15) ? s0[i] : -INFINITY; if (k == 8) s0[i] = (kk <= l15) ? s0[i] : -INFINITY; if (k == 9) s0[i] = -INFINITY;
;                         if (k == 1) s1[i] = (kk >= l15) ? s1[i] : -INFINITY; if (k == 9) s1[i] = (kk <= l15) ? s1[i] : -INFINITY; if (k == 0) s1[i] = -INFINITY;
;                         mx[0] = fmaxf(mx[0], s0[i]); mx[1] = fmaxf(mx[1], s1[i]); }
.LBB0_231:
	s_and_b64 s[0:1], s[20:21], exec
	s_cselect_b32 s0, s63, 0
	s_add_i32 s36, s39, s0
	s_lshl_b32 s26, s38, 1
	s_and_b32 s27, s87, 2
	s_and_b64 s[0:1], s[50:51], exec
	s_cselect_b32 s27, s27, 0
	s_and_b64 s[0:1], exec, s[48:49]
	s_cselect_b32 s0, s26, s27
	s_add_i32 s53, s0, s63
	s_cmp_lg_u32 s44, 2
	s_cselect_b64 s[26:27], -1, 0
	s_cmp_eq_u32 s44, 2
	s_cselect_b64 s[0:1], -1, 0
	s_and_b64 s[38:39], s[0:1], exec
	s_cselect_b32 s92, 0, s53
	s_cselect_b32 s53, s70, s69
	s_cmp_lg_u32 s92, 0
	s_cselect_b64 s[38:39], -1, 0
	s_add_i32 s25, s25, s63
	s_and_b64 s[26:27], s[26:27], s[38:39]
	s_lshl_b32 s25, s25, 7
	s_and_b64 s[20:21], s[20:21], exec
	s_cselect_b32 s20, 0, s25
	v_or_b32_e32 v134, s20, v164
	s_add_u32 s20, s22, s36
	v_lshlrev_b64 v[48:49], s93, v[134:135]
	v_or_b32_e32 v134, 16, v134
	s_addc_u32 s21, s23, 0
	s_ashr_i32 s25, s24, 31
	v_lshlrev_b64 v[58:59], s93, v[134:135]
	s_lshl_b64 s[22:23], s[24:25], 21
	v_lshl_add_u64 v[48:49], s[20:21], 0, v[48:49]
	v_lshl_add_u64 v[58:59], s[20:21], 0, v[58:59]
	v_lshl_add_u64 v[56:57], v[136:137], 0, s[22:23]
	v_lshlrev_b64 v[48:49], 7, v[48:49]
	v_lshlrev_b64 v[58:59], 7, v[58:59]
	v_lshl_add_u64 v[52:53], v[56:57], 0, v[48:49]
	v_lshl_add_u64 v[60:61], v[56:57], 0, v[58:59]
	global_load_dwordx4 v[48:51], v[52:53], off nt
	s_nop 0
	global_load_dwordx4 v[52:55], v[52:53], off offset:64 nt
	s_nop 0
	global_load_dwordx4 v[56:59], v[60:61], off nt
	s_nop 0
	global_load_dwordx4 v[60:63], v[60:61], off offset:64 nt
	v_or_b32_e32 v169, s53, v152
	v_cndmask_b32_e64 v81, 0, 1, s[26:27]
	v_or_b32_e32 v80, s59, v169
	v_mov_b32_e32 v134, 0xff800000
	v_cmp_ne_u32_e64 s[20:21], 1, v81
	s_andn2_b64 vcc, exec, s[26:27]
	v_mov_b32_e32 v133, 0xff800000
	v_mov_b32_e32 v170, 0xff800000
	v_mov_b32_e32 v171, 0xff800000
	v_mov_b32_e32 v172, 0xff800000
	v_mov_b32_e32 v176, 0xff800000
	s_cbranch_vccnz .LBB0_233
	v_mad_u64_u32 v[86:87], s[22:23], v80, s68, v[138:139]
	ds_read_b128 v[82:85], v86
	ds_read_b128 v[86:89], v86 offset:64
	s_waitcnt lgkmcnt(1)
	v_mfma_f32_16x16x32_bf16 v[82:85], v[82:85], v[76:79], 0
	s_waitcnt lgkmcnt(0)
	v_mfma_f32_16x16x32_bf16 v[82:85], v[86:89], v[72:75], v[82:85]
	s_nop 7
	v_cndmask_b32_e64 v133, v82, v167, s[6:7]
	v_cndmask_b32_e64 v170, v83, v167, s[8:9]
	v_cndmask_b32_e64 v171, v84, v167, s[10:11]
	v_max3_f32 v81, v133, s89, v170
	v_cndmask_b32_e64 v172, v85, v167, s[12:13]
	v_max3_f32 v176, v81, v171, v172

; #define LAS __attribute__((address_space(3)))
;     __device__ __forceinline__ void fused(f32x4 (&acc)[2][2][4][2], const Unit& u, int wr, int wc, int fr, int fq, PG8_LAS unsigned char* lds, int wid, int lane) const {
;         const int row0 = u.pm * 256 + wr * 64 + fr, col0 = u.pn * 256 + wc * 32 + 8 * fq;
;         LAS float* PS = (LAS float*)lds;
;         LAS float* RS = (LAS float*)(lds + 4096);
; #pragma unroll
;         for (int ai = 0; ai < 2; ++ai)
; #pragma unroll
;             for (int mh = 0; mh < 2; ++mh) { f32x4 xv[2][2][2];
; #pragma unroll
;                 for (int mm = 0; mm < 2; ++mm)
; #pragma unroll
;                     for (int bj = 0; bj < 2; ++bj) { const size_t o = (size_t)(row0 + ai * 128 + (2 * mh + mm) * 16) * 1024 + col0 + bj * 128; xv[mm][bj][0] = *(const f32x4*)(x + o); xv[mm][bj][1] = *(const f32x4*)(x + o + 4); }
; #pragma unroll
;                 for (int mm = 0; mm < 2; ++mm) { const int m = 2 * mh + mm; float sq = 0.f;
; #pragma unroll
;                     for (int bj = 0; bj < 2; ++bj)
; #pragma unroll
;                         for (int n = 0; n < 2; ++n) { const f32x4 v = acc[ai][bj][m][n] + xv[mm][bj][n]; acc[ai][bj][m][n] = v; sq += (v[0] * v[0] + v[1] * v[1]) + (v[2] * v[2] + v[3] * v[3]); }
;                     sq += __shfl_xor(sq, 16); sq += __shfl_xor(sq, 32);
;                     if (fq == 0) PS[(ai * 128 + wr * 64 + m * 16 + fr) * 4 + wc] = sq; } }
.LBB0_688:
	s_lshl_b32 s12, s6, 8
	s_add_i32 s1, s12, s38
	s_lshl_b32 s0, s7, 5
	v_or_b32_e32 v152, s1, v149
	s_lshl_b32 s1, s8, 8
	s_or_b32 s0, s1, s0
	v_and_or_b32 v144, v148, 24, s0
	v_ashrrev_i32_e32 v145, 31, v144
	v_ashrrev_i32_e32 v153, 31, v152
	v_lshl_add_u64 v[154:155], v[144:145], 2, s[56:57]
	v_lshlrev_b64 v[128:129], 12, v[152:153]
	v_lshl_add_u64 v[128:129], v[154:155], 0, v[128:129]
	s_barrier
	global_load_dwordx4 v[146:149], v[128:129], off
	global_load_dwordx4 v[160:163], v[128:129], off offset:16 nt
	global_load_dwordx4 v[164:167], v[128:129], off offset:512
	global_load_dwordx4 v[168:171], v[128:129], off offset:528 nt
	v_or_b32_e32 v128, 16, v152
	v_ashrrev_i32_e32 v129, 31, v128
	v_lshlrev_b64 v[128:129], 12, v[128:129]
	v_lshl_add_u64 v[132:133], v[154:155], 0, v[128:129]
	global_load_dwordx4 v[136:139], v[132:133], off offset:16 nt
	global_load_dwordx4 v[140:143], v[132:133], off
	global_load_dwordx4 v[128:131], v[132:133], off offset:528 nt
	s_nop 0
	global_load_dwordx4 v[132:135], v[132:133], off offset:512
	v_mbcnt_lo_u32_b32 v150, -1, 0
	v_mbcnt_hi_u32_b32 v150, -1, v150
	v_and_b32_e32 v158, 64, v150
	v_xor_b32_e32 v151, 16, v150
	v_add_u32_e32 v159, 64, v158
	v_cmp_lt_i32_e32 vcc, v151, v159
	s_lshl_b32 s2, s7, 2
	v_and_b32_e32 v157, 63, v188
	v_cndmask_b32_e32 v151, v150, v151, vcc
	v_lshlrev_b32_e32 v158, 2, v151
	s_add_i32 s2, s2, 0
	v_cmp_gt_u32_e64 s[0:1], 16, v157
	s_waitcnt vmcnt(0)
	v_pk_add_f32 v[126:127], v[126:127], v[148:149]
	v_pk_add_f32 v[124:125], v[124:125], v[146:147]
	v_pk_add_f32 v[122:123], v[122:123], v[162:163]
	v_pk_add_f32 v[120:121], v[120:121], v[160:161]
	v_pk_add_f32 v[118:119], v[118:119], v[166:167]
	v_pk_add_f32 v[116:117], v[116:117], v[164:165]
	v_mul_f32_e32 v146, v125, v125
	v_mul_f32_e32 v147, v127, v127
	v_mul_f32_e32 v148, v121, v121
	v_mul_f32_e32 v149, v123, v123
	v_pk_add_f32 v[114:115], v[114:115], v[170:171]
	v_pk_add_f32 v[112:113], v[112:113], v[168:169]
	v_mul_f32_e32 v151, v117, v117
	v_mul_f32_e32 v160, v119, v119
	v_fmac_f32_e32 v146, v124, v124
	v_fmac_f32_e32 v147, v126, v126
	v_fmac_f32_e32 v148, v120, v120
	v_fmac_f32_e32 v149, v122, v122
	v_mul_f32_e32 v161, v113, v113
	v_mul_f32_e32 v162, v115, v115
	v_fmac_f32_e32 v151, v116, v116
	v_fmac_f32_e32 v160, v118, v118
	v_add_f32_e32 v146, v146, v147
	v_add_f32_e32 v147, v148, v149
	v_fmac_f32_e32 v161, v112, v112
	v_fmac_f32_e32 v162, v114, v114
	v_add_f32_e32 v148, v151, v160
	v_add_f32_e32 v146, v146, v147
	v_add_f32_e32 v146, v146, v148
	v_add_f32_e32 v147, v161, v162
	v_add_f32_e32 v146, v146, v147
	ds_bpermute_b32 v147, v158, v146
	v_xor_b32_e32 v148, 32, v150
	v_cmp_lt_i32_e32 vcc, v148, v159
	v_lshl_add_u32 v159, v156, 4, s2
	s_waitcnt lgkmcnt(0)
	v_add_f32_e32 v146, v146, v147
	v_cndmask_b32_e32 v148, v150, v148, vcc
	v_lshlrev_b32_e32 v160, 2, v148
	ds_bpermute_b32 v147, v160, v146
	s_and_saveexec_b64 s[2:3], s[0:1]
	s_cbranch_execz .LBB0_690
	s_waitcnt lgkmcnt(0)
	v_add_f32_e32 v146, v146, v147
	ds_write_b32 v159, v146

;     __device__ __forceinline__ void fused(f32x4 (&acc)[2][2][4][2], const Unit& u, int wr, int wc, int fr, int fq, PG8_LAS unsigned char* lds, int wid, int lane) const {
;     ...
;             for (int mh = 0; mh < 2; ++mh) { f32x4 xv[2][2][2];
; #pragma unroll
;                 for (int mm = 0; mm < 2; ++mm)
; #pragma unroll
;                     for (int bj = 0; bj < 2; ++bj) { const size_t o = (size_t)(row0 + ai * 128 + (2 * mh + mm) * 16) * 1024 + col0 + bj * 128; xv[mm][bj][0] = *(const f32x4*)(x + o); xv[mm][bj][1] = *(const f32x4*)(x + o + 4); }
; #pragma unroll
;                 for (int mm = 0; mm < 2; ++mm) { const int m = 2 * mh + mm; float sq = 0.f;
; #pragma unroll
;                     for (int bj = 0; bj < 2; ++bj)
; #pragma unroll
;                         for (int n = 0; n < 2; ++n) { const f32x4 v = acc[ai][bj][m][n] + xv[mm][bj][n]; acc[ai][bj][m][n] = v; sq += (v[0] * v[0] + v[1] * v[1]) + (v[2] * v[2] + v[3] * v[3]); }
;                     sq += __shfl_xor(sq, 16); sq += __shfl_xor(sq, 32);
;                     if (fq == 0) PS[(ai * 128 + wr * 64 + m * 16 + fr) * 4 + wc] = sq; } }
.LBB0_692:
	s_or_b64 exec, exec, s[2:3]
	v_or_b32_e32 v96, 32, v152
	s_waitcnt lgkmcnt(0)
	v_ashrrev_i32_e32 v97, 31, v96
	v_lshlrev_b64 v[96:97], 12, v[96:97]
	v_lshl_add_u64 v[96:97], v[154:155], 0, v[96:97]
	global_load_dwordx4 v[146:149], v[96:97], off
	global_load_dwordx4 v[162:165], v[96:97], off offset:16 nt
	global_load_dwordx4 v[166:169], v[96:97], off offset:512
	global_load_dwordx4 v[170:173], v[96:97], off offset:528 nt
	v_or_b32_e32 v96, 48, v152
	v_ashrrev_i32_e32 v97, 31, v96
	v_lshlrev_b64 v[96:97], 12, v[96:97]
	v_lshl_add_u64 v[100:101], v[154:155], 0, v[96:97]
	global_load_dwordx4 v[104:107], v[100:101], off offset:16 nt
	global_load_dwordx4 v[108:111], v[100:101], off
	global_load_dwordx4 v[96:99], v[100:101], off offset:528 nt
	s_nop 0
	global_load_dwordx4 v[100:103], v[100:101], off offset:512
	s_waitcnt vmcnt(7)
	v_pk_add_f32 v[94:95], v[94:95], v[148:149]
	v_pk_add_f32 v[92:93], v[92:93], v[146:147]
	s_waitcnt vmcnt(6)
	v_pk_add_f32 v[90:91], v[90:91], v[164:165]
	v_pk_add_f32 v[148:149], v[88:89], v[162:163]
	s_waitcnt vmcnt(5)
	v_pk_add_f32 v[146:147], v[86:87], v[168:169]
	v_pk_add_f32 v[150:151], v[84:85], v[166:167]
	v_mul_f32_e32 v84, v93, v93
	v_mul_f32_e32 v85, v95, v95
	v_mul_f32_e32 v86, v149, v149
	v_mul_f32_e32 v87, v91, v91
	s_waitcnt vmcnt(4)
	v_pk_add_f32 v[82:83], v[82:83], v[172:173]
	v_pk_add_f32 v[80:81], v[80:81], v[170:171]
	v_mul_f32_e32 v88, v151, v151
	v_mul_f32_e32 v89, v147, v147
	v_fmac_f32_e32 v84, v92, v92
	v_fmac_f32_e32 v85, v94, v94
	v_fmac_f32_e32 v86, v148, v148
	v_fmac_f32_e32 v87, v90, v90
	v_mul_f32_e32 v161, v81, v81
	v_mul_f32_e32 v162, v83, v83
	v_fmac_f32_e32 v88, v150, v150
	v_fmac_f32_e32 v89, v146, v146
	v_add_f32_e32 v84, v84, v85
	v_add_f32_e32 v85, v86, v87
	v_fmac_f32_e32 v161, v80, v80
	v_fmac_f32_e32 v162, v82, v82
	v_add_f32_e32 v86, v88, v89
	v_add_f32_e32 v84, v84, v85
	v_add_f32_e32 v84, v84, v86
	v_add_f32_e32 v85, v161, v162
	v_add_f32_e32 v84, v84, v85
	ds_bpermute_b32 v85, v158, v84
	s_waitcnt lgkmcnt(0)
	v_add_f32_e32 v84, v84, v85
	ds_bpermute_b32 v85, v160, v84
	s_and_saveexec_b64 s[2:3], s[0:1]
	s_cbranch_execz .LBB0_694
	s_waitcnt lgkmcnt(0)
	v_add_f32_e32 v84, v84, v85
	ds_write_b32 v159, v84 offset:512

;     __device__ __forceinline__ void fused(f32x4 (&acc)[2][2][4][2], const Unit& u, int wr, int wc, int fr, int fq, PG8_LAS unsigned char* lds, int wid, int lane) const {
;     ...
;             for (int mh = 0; mh < 2; ++mh) { f32x4 xv[2][2][2];
; #pragma unroll
;                 for (int mm = 0; mm < 2; ++mm)
; #pragma unroll
;                     for (int bj = 0; bj < 2; ++bj) { const size_t o = (size_t)(row0 + ai * 128 + (2 * mh + mm) * 16) * 1024 + col0 + bj * 128; xv[mm][bj][0] = *(const f32x4*)(x + o); xv[mm][bj][1] = *(const f32x4*)(x + o + 4); }
; #pragma unroll
;                 for (int mm = 0; mm < 2; ++mm) { const int m = 2 * mh + mm; float sq = 0.f;
; #pragma unroll
;                     for (int bj = 0; bj < 2; ++bj)
; #pragma unroll
;                         for (int n = 0; n < 2; ++n) { const f32x4 v = acc[ai][bj][m][n] + xv[mm][bj][n]; acc[ai][bj][m][n] = v; sq += (v[0] * v[0] + v[1] * v[1]) + (v[2] * v[2] + v[3] * v[3]); }
;                     sq += __shfl_xor(sq, 16); sq += __shfl_xor(sq, 32);
;                     if (fq == 0) PS[(ai * 128 + wr * 64 + m * 16 + fr) * 4 + wc] = sq; } }
.LBB0_696:
	s_or_b64 exec, exec, s[2:3]
	s_waitcnt lgkmcnt(0)
	v_lshlrev_b64 v[64:65], 12, v[152:153]
	v_lshl_add_u64 v[64:65], v[154:155], 0, v[64:65]
	s_mov_b64 s[2:3], 0x80000
	v_lshl_add_u64 v[66:67], v[64:65], 0, s[2:3]
	v_add_co_u32_e32 v68, vcc, 0x80000, v64
	global_load_dwordx4 v[162:165], v[66:67], off offset:16 nt
	global_load_dwordx4 v[166:169], v[66:67], off offset:512
	v_addc_co_u32_e32 v69, vcc, 0, v65, vcc
	global_load_dwordx4 v[170:173], v[68:69], off
	global_load_dwordx4 v[174:177], v[66:67], off offset:528 nt
	s_mov_b64 s[2:3], 0x90000
	v_lshl_add_u64 v[66:67], v[64:65], 0, s[2:3]
	v_add_co_u32_e32 v64, vcc, 0x90000, v64
	global_load_dwordx4 v[72:75], v[66:67], off offset:16 nt
	global_load_dwordx4 v[68:71], v[66:67], off offset:512
	v_addc_co_u32_e32 v65, vcc, 0, v65, vcc
	global_load_dwordx4 v[76:79], v[64:65], off
	s_nop 0
	global_load_dwordx4 v[64:67], v[66:67], off offset:528 nt
	s_waitcnt vmcnt(7)
	v_pk_add_f32 v[62:63], v[62:63], v[164:165]
	v_pk_add_f32 v[60:61], v[60:61], v[162:163]
	s_waitcnt vmcnt(6)
	v_pk_add_f32 v[54:55], v[54:55], v[168:169]
	v_pk_add_f32 v[52:53], v[52:53], v[166:167]
	s_waitcnt vmcnt(5)
	v_pk_add_f32 v[58:59], v[58:59], v[172:173]
	v_pk_add_f32 v[102:103], v[56:57], v[170:171]
	v_mul_f32_e32 v56, v61, v61
	v_mul_f32_e32 v57, v63, v63
	v_mul_f32_e32 v106, v53, v53
	v_mul_f32_e32 v107, v55, v55
	v_mul_f32_e32 v110, v103, v103
	v_mul_f32_e32 v111, v59, v59
	s_waitcnt vmcnt(4)
	v_pk_add_f32 v[50:51], v[50:51], v[176:177]
	v_pk_add_f32 v[48:49], v[48:49], v[174:175]
	v_fmac_f32_e32 v56, v60, v60
	v_fmac_f32_e32 v57, v62, v62
	v_fmac_f32_e32 v106, v52, v52
	v_fmac_f32_e32 v107, v54, v54
	v_fmac_f32_e32 v110, v102, v102
	v_fmac_f32_e32 v111, v58, v58
	v_mul_f32_e32 v161, v49, v49
	v_mul_f32_e32 v162, v51, v51
	v_add_f32_e32 v56, v56, v57
	v_add_f32_e32 v57, v106, v107
	v_add_f32_e32 v106, v110, v111
	v_fmac_f32_e32 v161, v48, v48
	v_fmac_f32_e32 v162, v50, v50
	v_add_f32_e32 v56, v106, v56
	v_add_f32_e32 v56, v56, v57
	v_add_f32_e32 v57, v161, v162
	v_add_f32_e32 v56, v56, v57
	ds_bpermute_b32 v57, v158, v56
	s_waitcnt lgkmcnt(0)
	v_add_f32_e32 v56, v56, v57
	ds_bpermute_b32 v57, v160, v56
	s_and_saveexec_b64 s[2:3], s[0:1]
	s_cbranch_execz .LBB0_698
	s_waitcnt lgkmcnt(0)
	v_add_f32_e32 v56, v56, v57
	ds_write_b32 v159, v56 offset:2048

;     __device__ __forceinline__ void fused(f32x4 (&acc)[2][2][4][2], const Unit& u, int wr, int wc, int fr, int fq, PG8_LAS unsigned char* lds, int wid, int lane) const {
;     ...
;             for (int mh = 0; mh < 2; ++mh) { f32x4 xv[2][2][2];
; #pragma unroll
;                 for (int mm = 0; mm < 2; ++mm)
; #pragma unroll
;                     for (int bj = 0; bj < 2; ++bj) { const size_t o = (size_t)(row0 + ai * 128 + (2 * mh + mm) * 16) * 1024 + col0 + bj * 128; xv[mm][bj][0] = *(const f32x4*)(x + o); xv[mm][bj][1] = *(const f32x4*)(x + o + 4); }
; #pragma unroll
;                 for (int mm = 0; mm < 2; ++mm) { const int m = 2 * mh + mm; float sq = 0.f;
; #pragma unroll
;                     for (int bj = 0; bj < 2; ++bj)
; #pragma unroll
;                         for (int n = 0; n < 2; ++n) { const f32x4 v = acc[ai][bj][m][n] + xv[mm][bj][n]; acc[ai][bj][m][n] = v; sq += (v[0] * v[0] + v[1] * v[1]) + (v[2] * v[2] + v[3] * v[3]); }
;                     sq += __shfl_xor(sq, 16); sq += __shfl_xor(sq, 32);
;                     if (fq == 0) PS[(ai * 128 + wr * 64 + m * 16 + fr) * 4 + wc] = sq; } }
.LBB0_700:
	s_or_b64 exec, exec, s[2:3]
	s_waitcnt lgkmcnt(0)
	v_lshlrev_b64 v[32:33], 12, v[152:153]
	v_lshl_add_u64 v[32:33], v[154:155], 0, v[32:33]
	s_mov_b64 s[2:3], 0xa0000
	v_lshl_add_u64 v[34:35], v[32:33], 0, s[2:3]
	v_add_co_u32_e32 v36, vcc, 0xa0000, v32
	global_load_dwordx4 v[152:155], v[34:35], off offset:16 nt
	global_load_dwordx4 v[162:165], v[34:35], off offset:512
	v_addc_co_u32_e32 v37, vcc, 0, v33, vcc
	global_load_dwordx4 v[166:169], v[36:37], off
	global_load_dwordx4 v[170:173], v[34:35], off offset:528 nt
	s_mov_b64 s[2:3], 0xb0000
	v_lshl_add_u64 v[34:35], v[32:33], 0, s[2:3]
	v_add_co_u32_e32 v32, vcc, 0xb0000, v32
	global_load_dwordx4 v[40:43], v[34:35], off offset:16 nt
	global_load_dwordx4 v[36:39], v[34:35], off offset:512
	v_addc_co_u32_e32 v33, vcc, 0, v33, vcc
	global_load_dwordx4 v[44:47], v[32:33], off
	s_nop 0
	global_load_dwordx4 v[32:35], v[34:35], off offset:528 nt
	s_waitcnt vmcnt(7)
	v_pk_add_f32 v[30:31], v[30:31], v[154:155]
	v_pk_add_f32 v[28:29], v[28:29], v[152:153]
	s_waitcnt vmcnt(6)
	v_pk_add_f32 v[22:23], v[22:23], v[164:165]
	v_pk_add_f32 v[20:21], v[20:21], v[162:163]
	s_waitcnt vmcnt(5)
	v_pk_add_f32 v[26:27], v[26:27], v[168:169]
	v_pk_add_f32 v[74:75], v[24:25], v[166:167]
	v_mul_f32_e32 v24, v29, v29
	v_mul_f32_e32 v25, v31, v31
	v_mul_f32_e32 v106, v21, v21
	v_mul_f32_e32 v107, v23, v23
	v_mul_f32_e32 v110, v75, v75
	v_mul_f32_e32 v111, v27, v27
	s_waitcnt vmcnt(4)
	v_pk_add_f32 v[18:19], v[18:19], v[172:173]
	v_pk_add_f32 v[16:17], v[16:17], v[170:171]
	v_fmac_f32_e32 v24, v28, v28
	v_fmac_f32_e32 v25, v30, v30
	v_fmac_f32_e32 v106, v20, v20
	v_fmac_f32_e32 v107, v22, v22
	v_fmac_f32_e32 v110, v74, v74
	v_fmac_f32_e32 v111, v26, v26
	v_mul_f32_e32 v152, v17, v17
	v_mul_f32_e32 v153, v19, v19
	v_add_f32_e32 v24, v24, v25
	v_add_f32_e32 v25, v106, v107
	v_add_f32_e32 v106, v110, v111
	v_fmac_f32_e32 v152, v16, v16
	v_fmac_f32_e32 v153, v18, v18
	v_add_f32_e32 v24, v106, v24
	v_add_f32_e32 v24, v24, v25
	v_add_f32_e32 v25, v152, v153
	v_add_f32_e32 v24, v24, v25
	ds_bpermute_b32 v25, v158, v24
	s_waitcnt lgkmcnt(0)
	v_add_f32_e32 v24, v24, v25
	ds_bpermute_b32 v25, v160, v24
	s_and_saveexec_b64 s[2:3], s[0:1]
	s_cbranch_execz .LBB0_702
	s_waitcnt lgkmcnt(0)
	v_add_f32_e32 v24, v24, v25
	ds_write_b32 v159, v24 offset:2560
